# attention: K/V prefetch no longer waited for at the unit's first MFMA / first softmax (sink loaded a unit ahead, no-next path drains explicitly, vmcnt(1)/vmcnt(0) -> vmcnt(8))
# speedup vs baseline: 1.0035x; 1.0008x over previous
; __device__ __forceinline__ void attn_phase(LAS unsigned char* lds, const bf16* PROJ, bf16* CONCAT, const float* sinks) {
;     ...
;     const bool xmap = (gridDim.x == 256);
;     ...
;     if ((int)blockIdx.x < NB * 64 * 2) { ATT_LOAD_KV(ATT_UNIT((int)blockIdx.x)); ATT_LOAD_Q(ATT_UNIT((int)blockIdx.x)); }
;     ...
;         const float sink = sinks[h];
.LBB0_261:
	s_or_b64 exec, exec, s[0:1]
	v_readlane_b32 s0, v244, 21
	v_readlane_b32 s1, v244, 22
	s_lshl_b32 s22, s0, 3
	v_readlane_b32 s0, v245, 30
	v_readlane_b32 s1, v245, 31
	s_xor_b64 s[20:21], s[18:19], -1
	v_mov_b32_e32 v70, v192
	v_cndmask_b32_e64 v0, 0, 1, s[0:1]
	v_cmp_ne_u32_e64 s[16:17], 1, v0
	s_andn2_b64 vcc, exec, s[0:1]
	s_waitcnt lgkmcnt(0)
	v_writelane_b32 v244, s16, 23
	s_barrier
	s_nop 0
	v_writelane_b32 v244, s17, 24
	s_cbranch_vccnz .LBB0_280
	v_readlane_b32 s100, v246, 41
	v_readlane_b32 s101, v246, 42
	v_readlane_b32 s99, v245, 40
	s_lshl_b32 s98, s22, 2
	s_add_u32 s100, s100, s98
	s_addc_u32 s101, s101, 0
	v_ashrrev_i32_e32 v250, 7, v192
	v_add_u32_e32 v250, s99, v250
	v_ashrrev_i32_e32 v251, 31, v250
	v_lshl_add_u64 v[250:251], v[250:251], 2, s[100:101]
	global_load_dword v249, v[250:251], off
	v_ashrrev_i32_e32 v71, 6, v70
	v_readlane_b32 s16, v245, 32
	v_lshlrev_b32_e32 v68, 3, v71
	v_readlane_b32 s0, v245, 38
	v_readlane_b32 s17, v245, 33
	v_readlane_b32 s38, v245, 36
	v_ashrrev_i32_e32 v69, 31, v68
	v_readlane_b32 s1, v245, 39
	v_cndmask_b32_e64 v0, 0, 1, s[16:17]
	v_readlane_b32 s39, v245, 37
	v_and_b32_e32 v128, 63, v70
	v_lshl_add_u64 v[28:29], v[68:69], 1, s[0:1]
	v_cmp_ne_u32_e64 s[0:1], 1, v0
	s_andn2_b64 vcc, exec, s[16:17]
	s_mul_i32 s16, s39, 0xa00
	s_cbranch_vccnz .LBB0_265
	v_or_b32_e32 v0, s38, v128
	v_mad_u64_u32 v[2:3], s[36:37], v0, s85, v[28:29]
	v_add_u32_e32 v3, s16, v3
	global_load_dwordx4 v[4:7], v[2:3], off offset:1024
	global_load_dwordx4 v[8:11], v[2:3], off offset:1280
	s_and_b64 vcc, exec, s[0:1]
	v_or_b32_e32 v129, 64, v128
	s_cbranch_vccnz .LBB0_266

; __device__ __forceinline__ void attn_phase(LAS unsigned char* lds, const bf16* PROJ, bf16* CONCAT, const float* sinks) {
;     ...
;     bf16x8 qf[4][2];
;     ...
;     const bool xmap = (gridDim.x == 256);
;     ...
;     if ((int)blockIdx.x < NB * 64 * 2) { ATT_LOAD_KV(ATT_UNIT((int)blockIdx.x)); ATT_LOAD_Q(ATT_UNIT((int)blockIdx.x)); }
.LBB0_267:
	v_or_b32_e32 v2, 0x80, v128
	v_mov_b32_e32 v3, v1
	v_lshl_add_u64 v[20:21], s[38:39], 0, v[2:3]
	v_or_b32_e32 v130, 0xc0, v128
	v_mov_b32_e32 v131, v1
	v_mad_u64_u32 v[24:25], s[0:1], v20, s85, v[28:29]
	v_lshl_add_u64 v[30:31], s[38:39], 0, v[130:131]
	v_mov_b32_e32 v0, v25
	v_mad_u64_u32 v[28:29], s[0:1], v30, s85, v[28:29]
	v_mad_u64_u32 v[20:21], s[0:1], v21, s85, v[0:1]
	v_mov_b32_e32 v0, v29
	v_mad_u64_u32 v[30:31], s[0:1], v31, s85, v[0:1]
	v_mov_b32_e32 v25, v20
	v_mov_b32_e32 v29, v30
	v_ashrrev_i32_e32 v133, 7, v70
	v_readlane_b32 s0, v245, 40
	global_load_dwordx4 v[20:23], v[24:25], off offset:1024
	s_nop 0
	global_load_dwordx4 v[24:27], v[24:25], off offset:1280
	s_nop 0
	global_load_dwordx4 v[64:67], v[28:29], off offset:1024
	global_load_dwordx4 v[60:63], v[28:29], off offset:1280
	v_add_lshl_u32 v28, v133, s0, 6
	v_ashrrev_i32_e32 v29, 31, v28
	v_bitop3_b32 v132, v70, 15, 64 bitop3:0xe0
	v_readlane_b32 s0, v245, 41
	v_lshl_add_u64 v[28:29], v[28:29], 1, s[74:75]
	v_and_b32_e32 v0, 48, v128
	v_or_b32_e32 v30, s0, v132
	v_readlane_b32 s16, v245, 34
	v_lshl_add_u64 v[28:29], v[28:29], 0, v[0:1]
	v_readlane_b32 s17, v245, 35
	v_or_b32_e32 v30, s16, v30
	v_mad_u64_u32 v[32:33], s[0:1], v30, s85, v[28:29]
	s_mov_b32 s0, 0x1e000
	v_mad_i32_i24 v33, s17, v195, v33
	v_add_co_u32_e32 v28, vcc, s0, v32
	s_mov_b32 s0, 0x14000
	s_nop 0
	v_addc_co_u32_e32 v29, vcc, 0, v33, vcc
	global_load_dwordx4 v[52:55], v[28:29], off offset:64 nt
	global_load_dwordx4 v[56:59], v[28:29], off nt
	v_add_co_u32_e32 v28, vcc, s0, v32
	s_mov_b32 s0, 0xa000
	s_nop 0
	v_addc_co_u32_e32 v29, vcc, 0, v33, vcc
	global_load_dwordx4 v[44:47], v[28:29], off offset:64 nt
	global_load_dwordx4 v[48:51], v[28:29], off nt
	v_add_co_u32_e32 v28, vcc, s0, v32
	v_lshlrev_b32_e32 v75, 1, v68
	s_nop 0
	v_addc_co_u32_e32 v29, vcc, 0, v33, vcc
	global_load_dwordx4 v[36:39], v[28:29], off offset:64 nt
	global_load_dwordx4 v[40:43], v[28:29], off nt
	s_nop 0
	global_load_dwordx4 v[28:31], v[32:33], off offset:64 nt
	s_nop 0
	global_load_dwordx4 v[32:35], v[32:33], off nt
	v_lshl_add_u64 v[136:137], v[68:69], 1, s[74:75]
	v_and_b32_e32 v68, 48, v70
	v_and_b32_e32 v69, 64, v196
	v_add_u32_e32 v76, 0, v68
	v_xor_b32_e32 v68, 16, v196
	v_add_u32_e32 v69, 64, v69
	v_cmp_lt_i32_e32 vcc, v68, v69
	v_lshrrev_b32_e32 v73, 4, v128
	s_mov_b32 s23, s77
	v_cndmask_b32_e32 v68, v196, v68, vcc
	v_lshlrev_b32_e32 v135, 2, v68
	v_xor_b32_e32 v68, 32, v196
	v_cmp_lt_i32_e32 vcc, v68, v69
	v_readlane_b32 s36, v246, 27
	v_lshlrev_b32_e32 v74, 3, v73
	v_cndmask_b32_e32 v68, v196, v68, vcc
	v_lshlrev_b32_e32 v73, 2, v73
	v_lshlrev_b32_e32 v148, 2, v68
	v_bfe_u32 v68, v70, 2, 2
	s_lshl_b64 s[0:1], s[22:23], 2
	v_readlane_b32 s50, v246, 41
	v_or_b32_e32 v77, v73, v68
	v_lshlrev_b32_e32 v68, 3, v70
	v_lshl_add_u64 v[140:141], s[74:75], 0, v[0:1]
	v_mul_u32_u24_e32 v0, 0x48, v128
	v_readlane_b32 s51, v246, 42
	s_add_u32 s0, s50, s0
	v_and_b32_e32 v68, 24, v68
	v_lshlrev_b32_e32 v0, 1, v0
	s_movk_i32 s16, 0x1200
	s_addc_u32 s1, s51, s1
	v_add_u32_e32 v78, 0, v68
	v_lshlrev_b32_e32 v68, 4, v70
	v_add3_u32 v149, 0, v75, v0
	v_mul_lo_u32 v0, v71, s16
	s_add_i32 s16, 0, 0x12000
	v_and_b32_e32 v68, 0x70, v68
	v_mov_b32_e32 v69, v1
	v_add_u32_e32 v0, s16, v0
	v_readlane_b32 s42, v246, 33
	v_readlane_b32 s43, v246, 34
	v_and_b32_e32 v72, 15, v70
	v_lshl_add_u64 v[138:139], s[24:25], 0, v[68:69]
	v_add_u32_e32 v69, v0, v68
	v_or_b32_e32 v68, 2, v73
	v_readlane_b32 s44, v246, 35
	v_readlane_b32 s45, v246, 36
	v_and_b32_e32 v134, 64, v70
	v_cmp_lt_u32_e64 s[42:43], v72, v68
	v_or_b32_e32 v68, 3, v73
	v_readlane_b32 s38, v246, 29
	v_readlane_b32 s39, v246, 30
	v_readlane_b32 s40, v246, 31
	v_readlane_b32 s41, v246, 32
	v_readlane_b32 s48, v246, 39
	v_readlane_b32 s49, v246, 40
	v_lshrrev_b32_e32 v80, 3, v128
	v_cmp_lt_u32_e64 s[44:45], v72, v68
	v_or_b32_e32 v68, v77, v134
	v_or_b32_e32 v75, 32, v134
	v_mul_u32_u24_e32 v79, 0x90, v72
	v_cmp_lt_u32_e64 s[38:39], v72, v73
	v_cmp_ge_u32_e64 s[40:41], v73, v72
	v_cmp_lt_u32_e64 s[48:49], v73, v72
	v_mul_u32_u24_e32 v73, 0x90, v68
	v_or_b32_e32 v68, 8, v80
	v_or_b32_e32 v72, v75, v72
	v_or_b32_e32 v75, v75, v77
	v_readlane_b32 s46, v246, 37
	v_readlane_b32 s47, v246, 38
	v_mul_u32_u24_e32 v70, 0x90, v80
	v_mul_u32_u24_e32 v71, 0x90, v132
	v_add3_u32 v150, v0, v79, v74
	v_lshlrev_b32_e32 v0, 10, v80
	v_mul_u32_u24_e32 v74, 0x90, v68
	v_lshlrev_b32_e32 v68, 10, v68
	v_mul_u32_u24_e32 v72, 0x90, v72
	v_mul_u32_u24_e32 v75, 0x90, v75
	v_cmp_ne_u32_e64 s[46:47], 0, v134
	v_add_u32_e32 v151, v76, v71
	v_add_u32_e32 v152, v78, v73
	v_add_u32_e32 v153, v69, v70
	v_lshlrev_b32_e32 v0, 1, v0
	v_add_u32_e32 v154, v69, v74
	v_lshlrev_b32_e32 v142, 1, v68
	v_add_u32_e32 v155, v76, v72
	v_add_u32_e32 v156, v78, v75
	v_readlane_b32 s16, v245, 27
	s_mov_b32 s23, s2
	v_readlane_b32 s37, v246, 28
	s_waitcnt vmcnt(0)
	s_branch .LBB0_269

; #define LAS __attribute__((address_space(3)))
; #define LAS __attribute__((address_space(3)))
; __device__ __forceinline__ void attn_phase(LAS unsigned char* lds, const bf16* PROJ, bf16* CONCAT, const float* sinks) {
;     ...
;     for (int ul = blockIdx.x; ul < NB * 64 * 2; ul += gridDim.x) {
;         const int u = ATT_UNIT(ul);
;         const int kh = u & 1, n = (u >> 1) & 63, b = u >> 7;
;         const int g = wave >> 1, h = kh * 4 + g;
;         const size_t qrow0 = (size_t)b * SEQ + n * 128 + (wave & 1) * 64 + fr;
; #pragma unroll
;         for (int i = 0; i < 4; ++i) { const int kj = lane + 64 * i;
;             *(LAS v4u*)(Ks + kj * 72 + wave * 8) = kv[i];
;             *(LAS v4u*)(Vs + kj * 72 + wave * 8) = vv[i]; }
;         __syncthreads();
;         if (ul + (int)gridDim.x < NB * 64 * 2) ATT_LOAD_KV(ATT_UNIT(ul + (int)gridDim.x));
.LBB0_271:
	s_add_i32 s17, s23, s96
	s_cmpk_lt_i32 s17, 0x400
	s_cselect_b64 s[64:65], -1, 0
	s_cmpk_gt_i32 s17, 0x3ff
	s_cselect_b64 s[62:63], -1, 0
	s_and_b64 vcc, exec, s[62:63]
	s_waitcnt vmcnt(13)
	ds_write_b128 v149, v[4:7]
	s_waitcnt vmcnt(12)
	ds_write_b128 v149, v[8:11] offset:36864
	ds_write_b128 v149, v[12:15] offset:9216
	ds_write_b128 v149, v[16:19] offset:46080
	s_waitcnt vmcnt(11)
	ds_write_b128 v149, v[20:23] offset:18432
	s_waitcnt vmcnt(10)
	ds_write_b128 v149, v[24:27] offset:55296
	s_waitcnt vmcnt(9)
	ds_write_b128 v149, v[64:67] offset:27648
	s_waitcnt vmcnt(8)
	ds_write_b128 v149, v[60:63] offset:64512
	s_waitcnt lgkmcnt(0)
	s_barrier
	s_cbranch_vccz .Lattn_has_next
	s_waitcnt vmcnt(0)
	s_branch .LBB0_278
.Lattn_has_next:
	s_and_b32 s50, s17, 7
	s_lshl_b32 s50, s50, 7
	s_bfe_u32 s51, s17, 0x10009
	s_lshl_b32 s51, s51, 6
	s_or_b32 s50, s50, s51
	s_bfe_u32 s51, s17, 0x50003
	s_lshl_b32 s51, s51, 1
	s_or_b32 s50, s50, s51
	s_bfe_u32 s51, s17, 0x10008
	s_or_b32 s50, s50, s51
	s_and_b64 s[36:37], s[80:81], exec
	s_cselect_b32 s50, s50, s17
	s_mov_b32 s53, s50
	s_lshr_b32 s51, s50, 1
	s_and_b32 s54, s51, 63
	s_ashr_i32 s36, s50, 7
	s_ashr_i32 s37, s36, 31
	s_lshl_b64 s[36:37], s[36:37], 13
	s_lshl_b32 s55, s54, 7
	s_cmp_lg_u32 s54, 0
	s_cselect_b64 s[50:51], -1, 0
	s_or_b32 s36, s36, s55
	s_add_u32 s36, s36, 0xffffff80
	s_addc_u32 s37, s37, -1
	s_lshl_b32 s53, s53, 7
	s_and_b32 s76, s53, 0x80
	s_cmp_eq_u32 s54, 0
	v_lshl_add_u64 v[60:61], v[136:137], 0, s[76:77]
	s_mul_i32 s53, s37, 0xa00
	s_cbranch_scc1 .LBB0_275
	v_or_b32_e32 v4, s36, v128
	v_mad_u64_u32 v[8:9], s[54:55], v4, s85, v[60:61]
	v_add_u32_e32 v9, s53, v9
	global_load_dwordx4 v[4:7], v[8:9], off offset:1024
	s_nop 0
	global_load_dwordx4 v[8:11], v[8:9], off offset:1280
	s_andn2_b64 vcc, exec, s[50:51]
	s_cbranch_vccnz .LBB0_276

; #define LAS __attribute__((address_space(3)))
; #define LAS __attribute__((address_space(3)))
; #define ATT_LDK(t) do { kfr[t][0] = *(const LAS bf16x8*)(kp0 + (t) * 16 * 72); kfr[t][1] = *(const LAS bf16x8*)(kp0 + (t) * 16 * 72 + 32); } while (0)
; __device__ __forceinline__ void attn_phase(LAS unsigned char* lds, const bf16* PROJ, bf16* CONCAT, const float* sinks) {
;     ...
;         const float sink = sinks[h];
;         const int firstblk = (n == 0);
; #pragma unroll
;         for (int p = 0; p < 2; ++p) {
;             const int q16a = (wave & 1) * 4 + 2 * p, kt0 = q16a;
;             f32x4 st[2][10];
;             bf16x8 kfr[10][2];
;             const LAS bf16* kp0 = Ks + (16 * kt0 + fr) * 72 + 8 * fq;
;     ...
;             ATT_LDK(0);
; #pragma unroll
;             for (int t = 0; t < 10; ++t) {
;                 if (t + 1 < 10) ATT_LDK(t + 1);
; #pragma unroll
;                 for (int x = 0; x < 2; ++x) {
;                     if (x + 8 - t == 9 || x + 8 - t == -1) { st[x][t] = (f32x4){-1e30f, -1e30f, -1e30f, -1e30f}; continue; }
;                     f32x4 acc = (f32x4){0.f, 0.f, 0.f, 0.f};
;                     acc = __builtin_amdgcn_mfma_f32_16x16x32_bf16(kfr[t][0], qf[2 * p + x][0], acc, 0, 0, 0);
;                     acc = __builtin_amdgcn_mfma_f32_16x16x32_bf16(kfr[t][1], qf[2 * p + x][1], acc, 0, 0, 0);
;                     st[x][t] = acc;
;                 }
;             }
;     ...
;             float inv[2];
; #pragma unroll
;             for (int x = 0; x < 2; ++x) {
;                 float mx = -1e30f;
; #pragma unroll
;                 for (int t = 0; t < 10; ++t) {
;                     const int D = x + 8 - t;
;                     if (D == 9 || D == -1) continue;
;                     const bool tile_off = firstblk && (kt0 + t < 8);
; #pragma unroll
;                     for (int r = 0; r < 4; ++r) { const int dl = fr - 4 * fq - r;
;                         bool valid = !tile_off;
;                         if (D == 8) valid = valid && (dl < 0);
;                         if (D == 0) valid = valid && (dl >= 0);
;                         const float sv = valid ? st[x][t][r] : -1e30f; st[x][t][r] = sv; mx = fmaxf(mx, sv); }
.LBB0_278:
	s_lshl_b32 s37, s52, 2
	s_and_b32 s51, s37, 4
	v_add_u32_e32 v68, s51, v133
	v_ashrrev_i32_e32 v69, 31, v68
	v_lshlrev_b32_e32 v68, 6, v68
	v_ashrrev_i32_e32 v69, 31, v68
	v_lshl_add_u64 v[146:147], v[68:69], 1, v[138:139]
	ds_read_b128 v[68:71], v151
	ds_read_b128 v[72:75], v151 offset:64
	ds_read_b128 v[76:79], v151 offset:2304
	ds_read_b128 v[80:83], v151 offset:2368
	s_waitcnt vmcnt(8) lgkmcnt(3)
	v_mfma_f32_16x16x32_bf16 v[68:71], v[68:71], v[32:35], 0
	s_ashr_i32 s36, s52, 7
	s_bfe_u32 s50, s52, 0x60001
	s_ashr_i32 s37, s36, 31
	s_waitcnt lgkmcnt(2)
	v_mfma_f32_16x16x32_bf16 v[158:161], v[72:75], v[28:31], v[68:71]
	s_nop 2
	ds_read_b128 v[68:71], v151 offset:4608
	ds_read_b128 v[84:87], v151 offset:4672
	s_lshl_b32 s52, s50, 7
	s_lshl_b64 s[36:37], s[36:37], 13
	s_waitcnt lgkmcnt(3)
	v_mfma_f32_16x16x32_bf16 v[72:75], v[76:79], v[32:35], 0
	s_or_b32 s36, s36, s52
	s_cmp_lg_u32 s50, 0
	s_cselect_b64 s[60:61], -1, 0
	s_waitcnt lgkmcnt(2)
	v_mfma_f32_16x16x32_bf16 v[104:107], v[80:83], v[28:31], v[72:75]
	s_and_b64 s[50:51], s[60:61], s[38:39]
	s_and_b64 s[52:53], s[60:61], s[40:41]
	v_cndmask_b32_e64 v143, v197, v158, s[50:51]
	v_mfma_f32_16x16x32_bf16 v[72:75], v[76:79], v[40:43], 0
	v_cndmask_b32_e64 v157, v197, v159, s[52:53]
	s_and_b64 s[54:55], s[60:61], s[42:43]
	s_and_b64 s[56:57], s[60:61], s[44:45]
	v_mfma_f32_16x16x32_bf16 v[72:75], v[80:83], v[36:39], v[72:75]
	ds_read_b128 v[80:83], v151 offset:6912
	ds_read_b128 v[88:91], v151 offset:6976
	v_max3_f32 v145, v143, s78, v157
	v_cndmask_b32_e64 v158, v197, v160, s[54:55]
	s_waitcnt lgkmcnt(3)
	v_mfma_f32_16x16x32_bf16 v[76:79], v[68:71], v[32:35], 0
	v_cndmask_b32_e64 v159, v197, v161, s[56:57]
	v_max3_f32 v145, v145, v158, v159
	v_cndmask_b32_e64 v104, v197, v104, s[60:61]
	v_mfma_f32_16x16x32_bf16 v[68:71], v[68:71], v[40:43], 0
	v_cndmask_b32_e64 v105, v197, v105, s[60:61]
	v_max3_f32 v145, v145, v104, v105
	v_cndmask_b32_e64 v106, v197, v106, s[60:61]
	s_waitcnt lgkmcnt(2)
	v_mfma_f32_16x16x32_bf16 v[108:111], v[84:87], v[28:31], v[76:79]
	v_cndmask_b32_e64 v107, v197, v107, s[60:61]
	v_max3_f32 v145, v145, v106, v107
	s_or_b64 s[58:59], s[60:61], s[46:47]
	v_mfma_f32_16x16x32_bf16 v[76:79], v[84:87], v[36:39], v[68:71]
	s_nop 2
	ds_read_b128 v[68:71], v151 offset:9216
	ds_read_b128 v[84:87], v151 offset:9280
	v_cndmask_b32_e64 v108, v197, v108, s[60:61]
	v_cndmask_b32_e64 v109, v197, v109, s[60:61]
	s_waitcnt lgkmcnt(3)
	v_mfma_f32_16x16x32_bf16 v[92:95], v[80:83], v[32:35], 0
	v_max3_f32 v145, v145, v108, v109
	v_cndmask_b32_e64 v110, v197, v110, s[60:61]
	v_cndmask_b32_e64 v111, v197, v111, s[60:61]
	v_mfma_f32_16x16x32_bf16 v[80:83], v[80:83], v[40:43], 0
	v_max3_f32 v145, v145, v110, v111
	v_cndmask_b32_e64 v74, v197, v74, s[54:55]
	v_cndmask_b32_e64 v75, v197, v75, s[56:57]
	s_waitcnt lgkmcnt(2)
	v_mfma_f32_16x16x32_bf16 v[112:115], v[88:91], v[28:31], v[92:95]
	v_cndmask_b32_e64 v76, v197, v76, s[60:61]
	v_cndmask_b32_e64 v77, v197, v77, s[60:61]
	v_cndmask_b32_e64 v78, v197, v78, s[60:61]
	v_mfma_f32_16x16x32_bf16 v[80:83], v[88:91], v[36:39], v[80:83]
	ds_read_b128 v[88:91], v151 offset:11520
	ds_read_b128 v[92:95], v151 offset:11584
	s_nop 1
	v_cndmask_b32_e64 v160, v197, v112, s[60:61]
	v_cndmask_b32_e64 v161, v197, v113, s[60:61]
	s_waitcnt lgkmcnt(3)
	v_mfma_f32_16x16x32_bf16 v[96:99], v[68:71], v[32:35], 0
	v_max3_f32 v112, v145, v160, v161
	v_cndmask_b32_e64 v114, v197, v114, s[60:61]
	v_cndmask_b32_e64 v115, v197, v115, s[60:61]
	v_mfma_f32_16x16x32_bf16 v[68:71], v[68:71], v[40:43], 0
	v_max3_f32 v112, v112, v114, v115
	v_cndmask_b32_e64 v79, v197, v79, s[60:61]
	v_cndmask_b32_e64 v80, v197, v80, s[60:61]
	s_waitcnt lgkmcnt(2)
	v_mfma_f32_16x16x32_bf16 v[116:119], v[84:87], v[28:31], v[96:99]
	v_cndmask_b32_e64 v81, v197, v81, s[60:61]
	v_cndmask_b32_e64 v82, v197, v82, s[60:61]
	v_cndmask_b32_e64 v83, v197, v83, s[60:61]
	v_mfma_f32_16x16x32_bf16 v[84:87], v[84:87], v[36:39], v[68:71]
	s_nop 2
	ds_read_b128 v[68:71], v151 offset:13824
	ds_read_b128 v[96:99], v151 offset:13888
	v_cndmask_b32_e64 v116, v197, v116, s[58:59]
	v_cndmask_b32_e64 v117, v197, v117, s[58:59]
	s_waitcnt lgkmcnt(3)
	v_mfma_f32_16x16x32_bf16 v[100:103], v[88:91], v[32:35], 0
	v_max3_f32 v112, v112, v116, v117
	v_cndmask_b32_e64 v118, v197, v118, s[58:59]
	v_cndmask_b32_e64 v190, v197, v119, s[58:59]
	v_mfma_f32_16x16x32_bf16 v[88:91], v[88:91], v[40:43], 0
	v_max3_f32 v112, v112, v118, v190
	v_cndmask_b32_e64 v84, v197, v84, s[58:59]
	s_waitcnt lgkmcnt(2)
	v_mfma_f32_16x16x32_bf16 v[120:123], v[92:95], v[28:31], v[100:103]
	s_nop 2
	ds_read_b128 v[100:103], v151 offset:16128
	ds_read_b128 v[174:177], v151 offset:16192
	s_nop 2
	v_cndmask_b32_e64 v191, v197, v120, s[58:59]
	v_mfma_f32_16x16x32_bf16 v[88:91], v[92:95], v[36:39], v[88:91]
	v_cndmask_b32_e64 v199, v197, v121, s[58:59]
	v_max3_f32 v112, v112, v191, v199
	v_cndmask_b32_e64 v200, v197, v122, s[58:59]
	s_waitcnt lgkmcnt(3)
	v_mfma_f32_16x16x32_bf16 v[92:95], v[68:71], v[32:35], 0
	v_cndmask_b32_e64 v201, v197, v123, s[58:59]
	v_max3_f32 v112, v112, v200, v201
	v_mfma_f32_16x16x32_bf16 v[68:71], v[68:71], v[40:43], 0
	s_waitcnt lgkmcnt(2)
	v_mfma_f32_16x16x32_bf16 v[124:127], v[96:99], v[28:31], v[92:95]
	v_mfma_f32_16x16x32_bf16 v[92:95], v[96:99], v[36:39], v[68:71]
	s_nop 4
	ds_read_b128 v[68:71], v151 offset:18432
	ds_read_b128 v[178:181], v151 offset:18496
	v_cndmask_b32_e64 v202, v197, v124, s[58:59]
	v_cndmask_b32_e64 v203, v197, v125, s[58:59]
	s_waitcnt lgkmcnt(3)
	v_mfma_f32_16x16x32_bf16 v[96:99], v[100:103], v[32:35], 0
	v_max3_f32 v112, v112, v202, v203
	v_cndmask_b32_e64 v208, v197, v126, s[58:59]
	v_cndmask_b32_e64 v209, v197, v127, s[58:59]
	s_waitcnt lgkmcnt(1)
; __device__ __forceinline__ void attn_phase(LAS unsigned char* lds, const bf16* PROJ, bf16* CONCAT, const float* sinks) {
;     ...
;             float inv[2];
; #pragma unroll
;             for (int x = 0; x < 2; ++x) {
;                 float mx = -1e30f;
; #pragma unroll
;                 for (int t = 0; t < 10; ++t) {
;                     const int D = x + 8 - t;
;                     if (D == 9 || D == -1) continue;
;                     const bool tile_off = firstblk && (kt0 + t < 8);
; #pragma unroll
;                     for (int r = 0; r < 4; ++r) { const int dl = fr - 4 * fq - r;
;                         bool valid = !tile_off;
;                         if (D == 8) valid = valid && (dl < 0);
;                         if (D == 0) valid = valid && (dl >= 0);
;                         const float sv = valid ? st[x][t][r] : -1e30f; st[x][t][r] = sv; mx = fmaxf(mx, sv); }
;                 }
;                 mx = fmaxf(mx, __shfl_xor(mx, 16)); mx = fmaxf(mx, __shfl_xor(mx, 32)); mx = fmaxf(mx, sink);
;                 const float mb = mx * LOG2E;
;                 float lsum = 0.f;
; #pragma unroll
;                 for (int t = 0; t < 10; ++t) {
;                     const int D = x + 8 - t;
;                     if (D == 9 || D == -1) { st[x][t] = (f32x4){0.f, 0.f, 0.f, 0.f}; continue; }
; #pragma unroll
;                     for (int r = 0; r < 4; ++r) { const float pe = __builtin_amdgcn_exp2f(st[x][t][r] * LOG2E - mb); st[x][t][r] = pe; lsum += pe; }
;                 }
;                 lsum += __shfl_xor(lsum, 16); lsum += __shfl_xor(lsum, 32); lsum += __builtin_amdgcn_exp2f(sink * LOG2E - mb);
;                 inv[x] = 1.0f / lsum;
	v_mfma_f32_16x16x32_bf16 v[186:189], v[68:71], v[32:35], 0
	v_max3_f32 v112, v112, v208, v209
	v_mfma_f32_16x16x32_bf16 v[182:185], v[174:177], v[28:31], v[96:99]
	s_waitcnt lgkmcnt(0)
	v_mfma_f32_16x16x32_bf16 v[186:189], v[178:181], v[28:31], v[186:189]
	v_mfma_f32_16x16x32_bf16 v[96:99], v[100:103], v[40:43], 0
	s_nop 4
	v_cndmask_b32_e64 v182, v197, v182, s[58:59]
	v_cndmask_b32_e64 v183, v197, v183, s[58:59]
	v_max3_f32 v112, v112, v182, v183
	v_cndmask_b32_e64 v184, v197, v184, s[58:59]
	v_cndmask_b32_e64 v185, v197, v185, s[58:59]
	v_max3_f32 v112, v112, v184, v185
	v_cndmask_b32_e64 v186, v186, v197, s[38:39]
	v_cndmask_b32_e64 v187, v197, v187, s[48:49]
	v_max3_f32 v112, v112, v186, v187
	v_cndmask_b32_e64 v188, v188, v197, s[42:43]
	v_cndmask_b32_e64 v189, v189, v197, s[44:45]
	v_max3_f32 v112, v112, v188, v189
	ds_bpermute_b32 v113, v135, v112
	v_mfma_f32_16x16x32_bf16 v[96:99], v[174:177], v[36:39], v[96:99]
	ds_read_b128 v[100:103], v151 offset:20736
	ds_read_b128 v[174:177], v151 offset:20800
	s_waitcnt lgkmcnt(2)
	v_max_f32_e32 v113, v113, v113
	v_max_f32_e32 v112, v112, v113
	ds_bpermute_b32 v113, v148, v112
	s_waitcnt lgkmcnt(2)
	v_mfma_f32_16x16x32_bf16 v[100:103], v[100:103], v[40:43], 0
	v_cndmask_b32_e64 v210, v197, v99, s[58:59]
	s_waitcnt vmcnt(8) lgkmcnt(0)
	v_mov_b32_e32 v144, v249
	v_max3_f32 v145, v112, v113, v144
	v_pk_mul_f32 v[112:113], v[144:145], s[26:27] op_sel_hi:[1,0]
	v_mfma_f32_16x16x32_bf16 v[68:71], v[68:71], v[40:43], 0
	v_fma_f32 v119, v143, s26, -v113
	v_fma_f32 v120, v157, s26, -v113
	v_fma_f32 v104, v104, s26, -v113
	v_mfma_f32_16x16x32_bf16 v[100:103], v[174:177], v[36:39], v[100:103]
	v_exp_f32_e32 v174, v119
	v_exp_f32_e32 v175, v120
	v_fma_f32 v120, v158, s26, -v113
	v_exp_f32_e32 v176, v120
	v_fma_f32 v120, v159, s26, -v113
	v_exp_f32_e32 v177, v120
	v_mfma_f32_16x16x32_bf16 v[68:71], v[178:181], v[36:39], v[68:71]
	v_add_f32_e32 v119, 0, v174
	v_exp_f32_e32 v178, v104
	v_fma_f32 v105, v105, s26, -v113
	v_add_f32_e32 v119, v175, v119
	v_exp_f32_e32 v179, v105
	v_fma_f32 v105, v106, s26, -v113
	v_add_f32_e32 v119, v176, v119
	v_exp_f32_e32 v180, v105
	v_fma_f32 v105, v107, s26, -v113
	v_add_f32_e32 v119, v177, v119
	v_exp_f32_e32 v181, v105
	v_fma_f32 v105, v108, s26, -v113
	v_add_f32_e32 v104, v178, v119
	v_exp_f32_e32 v127, v105
	v_fma_f32 v105, v109, s26, -v113
	v_add_f32_e32 v104, v179, v104
	v_exp_f32_e32 v143, v105
	v_fma_f32 v105, v110, s26, -v113
	v_add_f32_e32 v104, v180, v104
	v_exp_f32_e32 v145, v105
	v_fma_f32 v105, v111, s26, -v113
	v_add_f32_e32 v104, v181, v104
	v_exp_f32_e32 v157, v105
	v_fma_f32 v105, v160, s26, -v113
	v_add_f32_e32 v104, v127, v104
	v_exp_f32_e32 v158, v105
	v_fma_f32 v105, v161, s26, -v113
	v_add_f32_e32 v104, v143, v104
	v_exp_f32_e32 v159, v105
	v_fma_f32 v105, v114, s26, -v113
	v_add_f32_e32 v104, v145, v104
	v_exp_f32_e32 v160, v105
	v_fma_f32 v105, v115, s26, -v113
	v_add_f32_e32 v104, v157, v104
	v_exp_f32_e32 v161, v105
	v_fma_f32 v105, v116, s26, -v113
	v_add_f32_e32 v104, v158, v104
	v_exp_f32_e32 v119, v105
	v_fma_f32 v105, v117, s26, -v113
	v_add_f32_e32 v104, v159, v104
	v_exp_f32_e32 v120, v105
	v_fma_f32 v105, v118, s26, -v113
	v_add_f32_e32 v104, v160, v104
	v_exp_f32_e32 v121, v105
	v_fma_f32 v105, v190, s26, -v113
	v_add_f32_e32 v104, v161, v104
	v_exp_f32_e32 v122, v105
	v_fma_f32 v105, v191, s26, -v113
	v_add_f32_e32 v104, v119, v104
	v_exp_f32_e32 v123, v105
	v_fma_f32 v105, v199, s26, -v113
	v_add_f32_e32 v104, v120, v104
	v_exp_f32_e32 v124, v105
	v_fma_f32 v105, v200, s26, -v113
	v_add_f32_e32 v104, v121, v104
	v_exp_f32_e32 v125, v105
	v_fma_f32 v105, v201, s26, -v113
	v_add_f32_e32 v104, v122, v104
	v_exp_f32_e32 v126, v105
	v_fma_f32 v105, v202, s26, -v113
	v_add_f32_e32 v104, v123, v104
	v_exp_f32_e32 v109, v105
	v_fma_f32 v105, v203, s26, -v113
	v_add_f32_e32 v104, v124, v104
	v_exp_f32_e32 v110, v105
	v_fma_f32 v105, v208, s26, -v113
	v_add_f32_e32 v104, v125, v104
	v_exp_f32_e32 v111, v105
	v_fma_f32 v105, v209, s26, -v113
	v_add_f32_e32 v104, v126, v104
	v_exp_f32_e32 v114, v105
	v_fma_f32 v105, v182, s26, -v113
	v_add_f32_e32 v104, v109, v104
	v_exp_f32_e32 v115, v105
	v_fma_f32 v105, v183, s26, -v113
	v_add_f32_e32 v104, v110, v104
	v_exp_f32_e32 v116, v105
	v_fma_f32 v105, v184, s26, -v113
	v_add_f32_e32 v104, v111, v104
	v_exp_f32_e32 v117, v105
	v_fma_f32 v105, v185, s26, -v113
	v_add_f32_e32 v104, v114, v104
	v_exp_f32_e32 v118, v105
	v_fma_f32 v105, v186, s26, -v113
	v_add_f32_e32 v104, v115, v104
	v_exp_f32_e32 v105, v105
	v_fma_f32 v106, v187, s26, -v113
	v_add_f32_e32 v104, v116, v104
	v_exp_f32_e32 v106, v106
	v_fma_f32 v107, v188, s26, -v113
	v_add_f32_e32 v104, v117, v104
	v_exp_f32_e32 v107, v107
	v_fma_f32 v108, v189, s26, -v113
	v_add_f32_e32 v104, v118, v104
	v_exp_f32_e32 v108, v108
	v_add_f32_e32 v104, v105, v104
	v_add_f32_e32 v104, v106, v104
	v_add_f32_e32 v104, v107, v104
	v_add_f32_e32 v104, v108, v104
	ds_bpermute_b32 v182, v135, v104
	v_sub_f32_e32 v113, v112, v113
	v_exp_f32_e32 v113, v113
	v_cndmask_b32_e64 v186, v197, v86, s[58:59]
	v_cndmask_b32_e64 v187, v197, v87, s[58:59]
	s_waitcnt lgkmcnt(0)
	v_add_f32_e32 v104, v104, v182
	ds_bpermute_b32 v182, v148, v104
	v_cndmask_b32_e64 v188, v197, v88, s[58:59]
	v_cndmask_b32_e64 v189, v197, v89, s[58:59]
	v_cndmask_b32_e64 v190, v197, v90, s[58:59]
	v_cndmask_b32_e64 v191, v197, v91, s[58:59]
	s_waitcnt lgkmcnt(0)
; __device__ __forceinline__ void attn_phase(LAS unsigned char* lds, const bf16* PROJ, bf16* CONCAT, const float* sinks) {
;     ...
;             for (int x = 0; x < 2; ++x) {
;                 float mx = -1e30f;
; #pragma unroll
;                 for (int t = 0; t < 10; ++t) {
;                     const int D = x + 8 - t;
;                     if (D == 9 || D == -1) continue;
;                     const bool tile_off = firstblk && (kt0 + t < 8);
; #pragma unroll
;                     for (int r = 0; r < 4; ++r) { const int dl = fr - 4 * fq - r;
;                         bool valid = !tile_off;
;                         if (D == 8) valid = valid && (dl < 0);
;                         if (D == 0) valid = valid && (dl >= 0);
;                         const float sv = valid ? st[x][t][r] : -1e30f; st[x][t][r] = sv; mx = fmaxf(mx, sv); }
;                 }
;                 mx = fmaxf(mx, __shfl_xor(mx, 16)); mx = fmaxf(mx, __shfl_xor(mx, 32)); mx = fmaxf(mx, sink);
;                 const float mb = mx * LOG2E;
;                 float lsum = 0.f;
; #pragma unroll
;                 for (int t = 0; t < 10; ++t) {
;                     const int D = x + 8 - t;
;                     if (D == 9 || D == -1) { st[x][t] = (f32x4){0.f, 0.f, 0.f, 0.f}; continue; }
; #pragma unroll
;                     for (int r = 0; r < 4; ++r) { const float pe = __builtin_amdgcn_exp2f(st[x][t][r] * LOG2E - mb); st[x][t][r] = pe; lsum += pe; }
;                 }
;                 lsum += __shfl_xor(lsum, 16); lsum += __shfl_xor(lsum, 32); lsum += __builtin_amdgcn_exp2f(sink * LOG2E - mb);
;                 inv[x] = 1.0f / lsum;
	v_add_f32_e32 v104, v104, v182
	v_add_f32_e32 v104, v113, v104
	v_div_scale_f32 v113, s[70:71], v104, v104, 1.0
	v_rcp_f32_e32 v182, v113
	v_cndmask_b32_e64 v199, v197, v92, s[58:59]
	v_cndmask_b32_e64 v200, v197, v93, s[58:59]
	v_cndmask_b32_e64 v201, v197, v94, s[58:59]
	v_fma_f32 v183, -v113, v182, 1.0
	v_fmac_f32_e32 v182, v183, v182
	v_div_scale_f32 v183, vcc, 1.0, v104, 1.0
	v_mul_f32_e32 v184, v183, v182
	v_fma_f32 v185, -v113, v184, v183
	v_fmac_f32_e32 v184, v185, v182
	v_fma_f32 v113, -v113, v184, v183
	v_div_fmas_f32 v113, v113, v182, v184
	v_div_fixup_f32 v104, v113, v104, 1.0
	v_cndmask_b32_e64 v113, v197, v72, s[50:51]
	v_cndmask_b32_e64 v184, v197, v73, s[52:53]
	v_max3_f32 v72, v113, s78, v184
	v_max3_f32 v72, v72, v74, v75
	v_max3_f32 v72, v72, v76, v77
	v_max3_f32 v72, v72, v78, v79
	v_max3_f32 v72, v72, v80, v81
	v_max3_f32 v72, v72, v82, v83
	v_cndmask_b32_e64 v185, v197, v85, s[58:59]
	v_max3_f32 v72, v72, v84, v185
	v_max3_f32 v72, v72, v186, v187
	v_max3_f32 v72, v72, v188, v189
	v_max3_f32 v72, v72, v190, v191
	v_max3_f32 v72, v72, v199, v200
	v_cndmask_b32_e64 v202, v197, v95, s[58:59]
	v_max3_f32 v72, v72, v201, v202
	v_cndmask_b32_e64 v203, v197, v96, s[58:59]
	v_cndmask_b32_e64 v208, v197, v97, s[58:59]
	v_max3_f32 v72, v72, v203, v208
	v_cndmask_b32_e64 v209, v197, v98, s[58:59]
	v_max3_f32 v72, v72, v209, v210
	v_max3_f32 v72, v72, v68, v69
	v_max3_f32 v73, v72, v70, v71
	v_cndmask_b32_e64 v211, v100, v197, s[38:39]
	v_cndmask_b32_e64 v212, v197, v101, s[48:49]
	v_cndmask_b32_e64 v72, v102, v197, s[42:43]
	v_cndmask_b32_e64 v213, v103, v197, s[44:45]
	v_max3_f32 v73, v73, v211, v212
	v_max3_f32 v73, v73, v72, v213
	ds_bpermute_b32 v85, v135, v73
	s_waitcnt lgkmcnt(0)
	v_max_f32_e32 v85, v85, v85
	v_max_f32_e32 v73, v73, v85
	ds_bpermute_b32 v85, v148, v73
	s_waitcnt lgkmcnt(0)
	v_max3_f32 v73, v73, v85, v144
	v_pk_mul_f32 v[182:183], v[72:73], s[26:27] op_sel_hi:[1,0]
	s_nop 0
	v_fma_f32 v72, v113, s26, -v183
	v_exp_f32_e32 v101, v72
	v_fma_f32 v73, v184, s26, -v183
	v_exp_f32_e32 v102, v73
	v_fma_f32 v73, v74, s26, -v183
	v_exp_f32_e32 v103, v73
	v_fma_f32 v73, v75, s26, -v183
	v_exp_f32_e32 v113, v73
	v_fma_f32 v73, v76, s26, -v183
	v_add_f32_e32 v72, 0, v101
	v_exp_f32_e32 v93, v73
	v_fma_f32 v73, v77, s26, -v183
	v_add_f32_e32 v72, v102, v72
	v_exp_f32_e32 v94, v73
	v_fma_f32 v73, v78, s26, -v183
	v_add_f32_e32 v72, v103, v72
	v_exp_f32_e32 v95, v73
	v_fma_f32 v73, v79, s26, -v183
	v_add_f32_e32 v72, v113, v72
	v_exp_f32_e32 v96, v73
	v_fma_f32 v73, v80, s26, -v183
	v_add_f32_e32 v72, v93, v72
	v_exp_f32_e32 v97, v73
	v_fma_f32 v73, v81, s26, -v183
	v_add_f32_e32 v72, v94, v72
	v_exp_f32_e32 v98, v73
	v_fma_f32 v73, v82, s26, -v183
	v_add_f32_e32 v72, v95, v72
	v_exp_f32_e32 v99, v73
	v_fma_f32 v73, v83, s26, -v183
	v_add_f32_e32 v72, v96, v72
	v_exp_f32_e32 v100, v73
	v_fma_f32 v73, v84, s26, -v183
	v_add_f32_e32 v72, v97, v72
	v_exp_f32_e32 v85, v73
	v_fma_f32 v73, v185, s26, -v183
	v_add_f32_e32 v72, v98, v72
	v_exp_f32_e32 v86, v73
	v_fma_f32 v73, v186, s26, -v183
	v_add_f32_e32 v72, v99, v72
	v_exp_f32_e32 v87, v73
	v_fma_f32 v73, v187, s26, -v183
	v_add_f32_e32 v72, v100, v72
	v_exp_f32_e32 v88, v73
	v_fma_f32 v73, v188, s26, -v183
	v_add_f32_e32 v72, v85, v72
	v_exp_f32_e32 v89, v73
	v_fma_f32 v73, v189, s26, -v183
	v_add_f32_e32 v72, v86, v72
	v_exp_f32_e32 v90, v73
	v_fma_f32 v73, v190, s26, -v183
	v_add_f32_e32 v72, v87, v72
	v_exp_f32_e32 v91, v73
	v_fma_f32 v73, v191, s26, -v183
	v_add_f32_e32 v72, v88, v72
	v_exp_f32_e32 v92, v73
	v_fma_f32 v73, v199, s26, -v183
	v_add_f32_e32 v72, v89, v72
	v_exp_f32_e32 v77, v73
	v_fma_f32 v73, v200, s26, -v183
	v_add_f32_e32 v72, v90, v72
	v_exp_f32_e32 v78, v73
	v_fma_f32 v73, v201, s26, -v183
	v_add_f32_e32 v72, v91, v72
	v_exp_f32_e32 v79, v73
	v_fma_f32 v73, v202, s26, -v183
	v_add_f32_e32 v72, v92, v72
	v_exp_f32_e32 v80, v73
	v_fma_f32 v73, v203, s26, -v183
	v_add_f32_e32 v72, v77, v72
	v_exp_f32_e32 v81, v73
	v_fma_f32 v73, v208, s26, -v183
	v_add_f32_e32 v72, v78, v72
	v_exp_f32_e32 v82, v73
	v_fma_f32 v73, v209, s26, -v183
	v_add_f32_e32 v72, v79, v72
	v_exp_f32_e32 v83, v73
	v_fma_f32 v73, v210, s26, -v183
	v_add_f32_e32 v72, v80, v72
	v_exp_f32_e32 v84, v73
	v_add_f32_e32 v72, v81, v72
	v_add_f32_e32 v72, v82, v72
	v_add_f32_e32 v72, v83, v72
	v_fma_f32 v68, v68, s26, -v183
	v_add_f32_e32 v73, v84, v72
	v_exp_f32_e32 v72, v68
	v_fma_f32 v69, v69, s26, -v183
	v_exp_f32_e32 v69, v69
	v_fma_f32 v70, v70, s26, -v183
	v_exp_f32_e32 v70, v70
	v_fma_f32 v71, v71, s26, -v183
	v_add_f32_e32 v68, v72, v73
	v_exp_f32_e32 v71, v71
	v_fma_f32 v73, v211, s26, -v183
	v_exp_f32_e32 v73, v73
	v_fma_f32 v74, v212, s26, -v183
	v_add_f32_e32 v68, v69, v68
	v_exp_f32_e32 v74, v74
	v_sub_f32_e32 v75, v182, v183
	v_add_f32_e32 v68, v70, v68
	v_exp_f32_e32 v75, v75
	v_fma_f32 v76, v213, s26, -v183
	v_add_f32_e32 v68, v71, v68
	v_exp_f32_e32 v76, v76
	v_add_f32_e32 v68, v73, v68
	v_add_f32_e32 v68, v74, v68
	v_add_f32_e32 v68, v75, v68
	v_add_f32_e32 v68, v76, v68
	ds_bpermute_b32 v182, v135, v68
	s_waitcnt lgkmcnt(0)
	v_add_f32_e32 v68, v68, v182
	ds_bpermute_b32 v182, v148, v68
	s_waitcnt lgkmcnt(0)
; #define LAS __attribute__((address_space(3)))
; #define LAS __attribute__((address_space(3)))
; __device__ __forceinline__ unsigned pk2(float lo, float hi) { return pg8::cvt_pk_bf16(lo, hi); }
; #define ATT_LDV(s) do { _Pragma("unroll") for (int dt = 0; dt < 4; ++dt) { vlo[s][dt] = lds_tr_a(vp0 + (s) * 32 * 72 + 16 * dt); vhi[s][dt] = lds_tr_a(vp0 + (s) * 32 * 72 + 16 * 72 + 16 * dt); } } while (0)
; __device__ __forceinline__ void attn_phase(LAS unsigned char* lds, const bf16* PROJ, bf16* CONCAT, const float* sinks) {
;     ...
;                 inv[x] = 1.0f / lsum;
;             }
;             f32x4 ot[2][4];
; #pragma unroll
;             for (int x = 0; x < 2; ++x)
; #pragma unroll
;                 for (int dt = 0; dt < 4; ++dt) ot[x][dt] = (f32x4){0.f, 0.f, 0.f, 0.f};
;             const LAS bf16* vp0 = Vs + (16 * kt0 + 4 * fq + (fr >> 2)) * 72 + 4 * (fr & 3);
;             v2u vlo[5][4], vhi[5][4];
;     ...
; #pragma unroll
;             for (int s2 = 0; s2 < 5; ++s2) {
;                 ATT_LDV(s2);
;                 bf16x8 pf[2];
; #pragma unroll
;                 for (int x = 0; x < 2; ++x) { v4u pw; pw.x = pk2(st[x][2 * s2][0], st[x][2 * s2][1]); pw.y = pk2(st[x][2 * s2][2], st[x][2 * s2][3]);
;                     pw.z = pk2(st[x][2 * s2 + 1][0], st[x][2 * s2 + 1][1]); pw.w = pk2(st[x][2 * s2 + 1][2], st[x][2 * s2 + 1][3]); pf[x] = __builtin_bit_cast(bf16x8, pw); }
; #pragma unroll
;                 for (int dt = 0; dt < 4; ++dt) {
;                     const bf16x8 vf = __builtin_bit_cast(bf16x8, (v4u){vlo[s2][dt].x, vlo[s2][dt].y, vhi[s2][dt].x, vhi[s2][dt].y});
; #pragma unroll
;                     for (int x = 0; x < 2; ++x) ot[x][dt] = __builtin_amdgcn_mfma_f32_16x16x32_bf16(vf, pf[x], ot[x][dt], 0, 0, 0);
;                 }
;             }
	v_add_f32_e32 v68, v68, v182
	v_sub_f32_e32 v182, v112, v183
	v_exp_f32_e32 v182, v182
	s_nop 0
	v_add_f32_e32 v68, v182, v68
	v_div_scale_f32 v182, s[70:71], v68, v68, 1.0
	v_rcp_f32_e32 v183, v182
	s_nop 0
	v_fma_f32 v184, -v182, v183, 1.0
	v_fmac_f32_e32 v183, v184, v183
	v_div_scale_f32 v184, vcc, 1.0, v68, 1.0
	v_mul_f32_e32 v185, v184, v183
	v_fma_f32 v186, -v182, v185, v184
	v_fmac_f32_e32 v185, v186, v183
	v_fma_f32 v182, -v182, v185, v184
	v_div_fmas_f32 v182, v182, v183, v185
	v_div_fixup_f32 v68, v182, v68, 1.0
	ds_read_b64_tr_b16 v[182:183], v152 offset:36864
	ds_read_b64_tr_b16 v[186:187], v152 offset:36896
	ds_read_b64_tr_b16 v[184:185], v152 offset:39168
	ds_read_b64_tr_b16 v[188:189], v152 offset:39200
	ds_read_b64_tr_b16 v[200:201], v152 offset:36928
	ds_read_b64_tr_b16 v[202:203], v152 offset:39232
	ds_read_b64_tr_b16 v[208:209], v152 offset:36960
	ds_read_b64_tr_b16 v[210:211], v152 offset:39264
	v_cvt_pk_bf16_f32 v174, v174, v175
	v_cvt_pk_bf16_f32 v175, v176, v177
	v_cvt_pk_bf16_f32 v176, v178, v179
	v_cvt_pk_bf16_f32 v177, v180, v181
	v_cvt_pk_bf16_f32 v178, v1, v1
	v_cvt_pk_bf16_f32 v179, v1, v1
	v_cvt_pk_bf16_f32 v180, v101, v102
	v_cvt_pk_bf16_f32 v181, v103, v113
	s_waitcnt lgkmcnt(5)
	v_mfma_f32_16x16x32_bf16 v[212:215], v[182:185], v[174:177], 0
	v_mfma_f32_16x16x32_bf16 v[182:185], v[182:185], v[178:181], 0
	s_waitcnt lgkmcnt(4)
	v_mfma_f32_16x16x32_bf16 v[216:219], v[186:189], v[174:177], 0
	v_mfma_f32_16x16x32_bf16 v[186:189], v[186:189], v[178:181], 0
	s_waitcnt lgkmcnt(2)
	v_mfma_f32_16x16x32_bf16 v[220:223], v[200:203], v[174:177], 0
	v_mfma_f32_16x16x32_bf16 v[200:203], v[200:203], v[178:181], 0
	s_waitcnt lgkmcnt(0)
	v_mfma_f32_16x16x32_bf16 v[174:177], v[208:211], v[174:177], 0
	v_mfma_f32_16x16x32_bf16 v[178:181], v[208:211], v[178:181], 0
	ds_read_b64_tr_b16 v[208:209], v152 offset:41472
	ds_read_b64_tr_b16 v[224:225], v152 offset:41504
	ds_read_b64_tr_b16 v[210:211], v152 offset:43776
	ds_read_b64_tr_b16 v[226:227], v152 offset:43808
	ds_read_b64_tr_b16 v[228:229], v152 offset:41536
	ds_read_b64_tr_b16 v[230:231], v152 offset:43840
	ds_read_b64_tr_b16 v[232:233], v152 offset:41568
	ds_read_b64_tr_b16 v[234:235], v152 offset:43872
	v_cvt_pk_bf16_f32 v236, v127, v143
	v_cvt_pk_bf16_f32 v237, v145, v157
	v_cvt_pk_bf16_f32 v238, v158, v159
	v_cvt_pk_bf16_f32 v239, v160, v161
	v_cvt_pk_bf16_f32 v94, v93, v94
	v_cvt_pk_bf16_f32 v95, v95, v96
	v_cvt_pk_bf16_f32 v96, v97, v98
	v_cvt_pk_bf16_f32 v97, v99, v100
	v_mov_b32_e32 v143, v1
	s_waitcnt lgkmcnt(5)
	v_mfma_f32_16x16x32_bf16 v[98:101], v[208:211], v[236:239], v[212:215]
	v_mfma_f32_16x16x32_bf16 v[158:161], v[208:211], v[94:97], v[182:185]
	s_waitcnt lgkmcnt(4)
	v_mfma_f32_16x16x32_bf16 v[182:185], v[224:227], v[236:239], v[216:219]
	v_mfma_f32_16x16x32_bf16 v[186:189], v[224:227], v[94:97], v[186:189]
	s_waitcnt lgkmcnt(2)
	v_mfma_f32_16x16x32_bf16 v[208:211], v[228:231], v[236:239], v[220:223]
	v_mfma_f32_16x16x32_bf16 v[200:203], v[228:231], v[94:97], v[200:203]
	s_waitcnt lgkmcnt(0)
	v_mfma_f32_16x16x32_bf16 v[94:97], v[232:235], v[94:97], v[178:181]
	s_nop 2
	ds_read_b64_tr_b16 v[178:179], v152 offset:46080
	ds_read_b64_tr_b16 v[212:213], v152 offset:46112
	ds_read_b64_tr_b16 v[180:181], v152 offset:48384
	ds_read_b64_tr_b16 v[214:215], v152 offset:48416
	ds_read_b64_tr_b16 v[216:217], v152 offset:46144
	ds_read_b64_tr_b16 v[218:219], v152 offset:48448
	ds_read_b64_tr_b16 v[220:221], v152 offset:46176
	ds_read_b64_tr_b16 v[222:223], v152 offset:48480
	v_cvt_pk_bf16_f32 v120, v119, v120
	v_cvt_pk_bf16_f32 v121, v121, v122
	v_mfma_f32_16x16x32_bf16 v[174:177], v[232:235], v[236:239], v[174:177]
	v_cvt_pk_bf16_f32 v122, v123, v124
	v_cvt_pk_bf16_f32 v123, v125, v126
	v_cvt_pk_bf16_f32 v86, v85, v86
	v_cvt_pk_bf16_f32 v87, v87, v88
	v_cvt_pk_bf16_f32 v88, v89, v90
	v_cvt_pk_bf16_f32 v89, v91, v92
	s_waitcnt lgkmcnt(5)
	v_mfma_f32_16x16x32_bf16 v[90:93], v[178:181], v[120:123], v[98:101]
	v_mfma_f32_16x16x32_bf16 v[98:101], v[178:181], v[86:89], v[158:161]
	s_waitcnt lgkmcnt(4)
	v_mfma_f32_16x16x32_bf16 v[124:127], v[212:215], v[120:123], v[182:185]
	v_mfma_f32_16x16x32_bf16 v[158:161], v[212:215], v[86:89], v[186:189]
	s_waitcnt lgkmcnt(2)
	v_mfma_f32_16x16x32_bf16 v[178:181], v[216:219], v[120:123], v[208:211]
	v_mfma_f32_16x16x32_bf16 v[182:185], v[216:219], v[86:89], v[200:203]
	s_waitcnt lgkmcnt(0)
	v_mfma_f32_16x16x32_bf16 v[120:123], v[220:223], v[120:123], v[174:177]
	v_mfma_f32_16x16x32_bf16 v[86:89], v[220:223], v[86:89], v[94:97]
	s_nop 2
	ds_read_b64_tr_b16 v[94:95], v152 offset:50688
	ds_read_b64_tr_b16 v[174:175], v152 offset:50720
	ds_read_b64_tr_b16 v[96:97], v152 offset:52992
	ds_read_b64_tr_b16 v[176:177], v152 offset:53024
	ds_read_b64_tr_b16 v[186:187], v152 offset:50752
	ds_read_b64_tr_b16 v[188:189], v152 offset:53056
	ds_read_b64_tr_b16 v[200:201], v152 offset:50784
	ds_read_b64_tr_b16 v[202:203], v152 offset:53088
	v_cvt_pk_bf16_f32 v208, v109, v110
	v_cvt_pk_bf16_f32 v209, v111, v114
	v_cvt_pk_bf16_f32 v210, v115, v116
	v_cvt_pk_bf16_f32 v211, v117, v118
	v_cvt_pk_bf16_f32 v78, v77, v78
	v_cvt_pk_bf16_f32 v79, v79, v80
	v_cvt_pk_bf16_f32 v80, v81, v82
	v_cvt_pk_bf16_f32 v81, v83, v84
	s_waitcnt lgkmcnt(5)
	v_mfma_f32_16x16x32_bf16 v[82:85], v[94:97], v[208:211], v[90:93]
	v_mfma_f32_16x16x32_bf16 v[90:93], v[94:97], v[78:81], v[98:101]
	s_waitcnt lgkmcnt(4)
	v_mfma_f32_16x16x32_bf16 v[94:97], v[174:177], v[208:211], v[124:127]
	v_mfma_f32_16x16x32_bf16 v[98:101], v[174:177], v[78:81], v[158:161]
	s_waitcnt lgkmcnt(2)
	v_mfma_f32_16x16x32_bf16 v[114:117], v[186:189], v[208:211], v[178:181]
	v_mfma_f32_16x16x32_bf16 v[124:127], v[186:189], v[78:81], v[182:185]
	s_waitcnt lgkmcnt(0)
; #define LAS __attribute__((address_space(3)))
; #define LAS __attribute__((address_space(3)))
; __device__ __forceinline__ unsigned pk2(float lo, float hi) { return pg8::cvt_pk_bf16(lo, hi); }
; #define ATT_LDK(t) do { kfr[t][0] = *(const LAS bf16x8*)(kp0 + (t) * 16 * 72); kfr[t][1] = *(const LAS bf16x8*)(kp0 + (t) * 16 * 72 + 32); } while (0)
; __device__ __forceinline__ void attn_phase(LAS unsigned char* lds, const bf16* PROJ, bf16* CONCAT, const float* sinks) {
;     ...
;         for (int p = 0; p < 2; ++p) {
;             const int q16a = (wave & 1) * 4 + 2 * p, kt0 = q16a;
;             f32x4 st[2][10];
;             bf16x8 kfr[10][2];
;             const LAS bf16* kp0 = Ks + (16 * kt0 + fr) * 72 + 8 * fq;
;     ...
;             ATT_LDK(0);
; #pragma unroll
;             for (int t = 0; t < 10; ++t) {
;                 if (t + 1 < 10) ATT_LDK(t + 1);
; #pragma unroll
;                 for (int x = 0; x < 2; ++x) {
;                     if (x + 8 - t == 9 || x + 8 - t == -1) { st[x][t] = (f32x4){-1e30f, -1e30f, -1e30f, -1e30f}; continue; }
;                     f32x4 acc = (f32x4){0.f, 0.f, 0.f, 0.f};
;                     acc = __builtin_amdgcn_mfma_f32_16x16x32_bf16(kfr[t][0], qf[2 * p + x][0], acc, 0, 0, 0);
;                     acc = __builtin_amdgcn_mfma_f32_16x16x32_bf16(kfr[t][1], qf[2 * p + x][1], acc, 0, 0, 0);
;                     st[x][t] = acc;
;                 }
;             }
;     ...
;             }
;     ...
; #pragma unroll
;             for (int x = 0; x < 2; ++x) {
;                 LAS bf16* stg = (LAS bf16*)(lds + 73728) + (wave * 2 + x) * (16 * 72);
; #pragma unroll
;                 for (int dt = 0; dt < 4; ++dt) *(LAS v2u*)(stg + fr * 72 + 16 * dt + 4 * fq) = (v2u){pk2(ot[x][dt][0] * inv[x], ot[x][dt][1] * inv[x]), pk2(ot[x][dt][2] * inv[x], ot[x][dt][3] * inv[x])};
;                 bf16* op = CONCAT + (qrow0 - fr + 16 * (2 * p + x)) * DM + h * 64;
; #pragma unroll
;                 for (int i = 0; i < 2; ++i) { const int row = 8 * i + (lane >> 3), chn = lane & 7;
;                     *(v4u*)(op + (size_t)row * DM + chn * 8) = *(const LAS v4u*)(stg + row * 72 + chn * 8); }
	v_mfma_f32_16x16x32_bf16 v[78:81], v[200:203], v[78:81], v[86:89]
	s_nop 2
	ds_read_b64_tr_b16 v[86:87], v152 offset:55296
	ds_read_b64_tr_b16 v[158:159], v152 offset:55328
	ds_read_b64_tr_b16 v[88:89], v152 offset:57600
	ds_read_b64_tr_b16 v[160:161], v152 offset:57632
	ds_read_b64_tr_b16 v[174:175], v152 offset:55360
	ds_read_b64_tr_b16 v[176:177], v152 offset:57664
	ds_read_b64_tr_b16 v[178:179], v152 offset:55392
	ds_read_b64_tr_b16 v[180:181], v152 offset:57696
	v_cvt_pk_bf16_f32 v106, v105, v106
	v_cvt_pk_bf16_f32 v107, v107, v108
	v_cvt_pk_bf16_f32 v108, v1, v1
	v_cvt_pk_bf16_f32 v109, v1, v1
	v_cvt_pk_bf16_f32 v182, v72, v69
	v_cvt_pk_bf16_f32 v183, v70, v71
	v_cvt_pk_bf16_f32 v184, v73, v74
	v_mfma_f32_16x16x32_bf16 v[118:121], v[200:203], v[208:211], v[120:123]
	v_cvt_pk_bf16_f32 v185, v75, v76
	s_waitcnt lgkmcnt(5)
	v_mfma_f32_16x16x32_bf16 v[70:73], v[86:89], v[106:109], v[82:85]
	s_waitcnt lgkmcnt(4)
	v_mfma_f32_16x16x32_bf16 v[82:85], v[158:161], v[106:109], v[94:97]
	v_mfma_f32_16x16x32_bf16 v[74:77], v[86:89], v[182:185], v[90:93]
	s_nop 4
	v_mul_f32_e32 v69, v104, v70
	v_mul_f32_e32 v70, v104, v71
	v_mul_f32_e32 v71, v104, v73
	s_waitcnt lgkmcnt(2)
	v_mfma_f32_16x16x32_bf16 v[90:93], v[174:177], v[106:109], v[114:117]
	v_cvt_pk_bf16_f32 v70, v69, v70
	v_mul_f32_e32 v69, v104, v72
	v_cvt_pk_bf16_f32 v71, v69, v71
	v_mfma_f32_16x16x32_bf16 v[86:89], v[158:161], v[182:185], v[98:101]
	ds_write_b64 v150, v[70:71]
	v_mul_f32_e32 v69, v104, v82
	v_mul_f32_e32 v70, v104, v83
	s_waitcnt lgkmcnt(1)
	v_mfma_f32_16x16x32_bf16 v[98:101], v[178:181], v[106:109], v[118:121]
	v_mul_f32_e32 v71, v104, v85
	v_cvt_pk_bf16_f32 v70, v69, v70
	v_mul_f32_e32 v69, v104, v84
	v_cvt_pk_bf16_f32 v71, v69, v71
	ds_write_b64 v150, v[70:71] offset:32
	v_mul_f32_e32 v69, v104, v90
	v_mul_f32_e32 v70, v104, v91
	v_mul_f32_e32 v71, v104, v93
	v_cvt_pk_bf16_f32 v70, v69, v70
	v_mul_f32_e32 v69, v104, v92
	v_cvt_pk_bf16_f32 v71, v69, v71
	ds_write_b64 v150, v[70:71] offset:64
	v_mul_f32_e32 v69, v104, v98
	v_mul_f32_e32 v70, v104, v99
	v_mul_f32_e32 v71, v104, v101
	v_cvt_pk_bf16_f32 v70, v69, v70
	v_mul_f32_e32 v69, v104, v100
	v_cvt_pk_bf16_f32 v71, v69, v71
	ds_write_b64 v150, v[70:71] offset:96
	v_mov_b32_e32 v71, s37
	v_or_b32_e32 v70, s36, v134
	v_lshlrev_b64 v[70:71], 11, v[70:71]
	v_lshl_add_u64 v[114:115], v[146:147], 0, v[70:71]
	ds_read_b128 v[70:73], v153
	v_lshl_add_u64 v[82:83], v[114:115], 0, v[0:1]
	v_mfma_f32_16x16x32_bf16 v[94:97], v[174:177], v[182:185], v[124:127]
	v_mul_f32_e32 v69, v68, v74
	s_mov_b64 s[36:37], 0x8000
	s_waitcnt lgkmcnt(0)
	global_store_dwordx4 v[82:83], v[70:73], off
	ds_read_b128 v[70:73], v154
	v_lshl_add_u64 v[82:83], v[114:115], 0, v[142:143]
	v_mfma_f32_16x16x32_bf16 v[78:81], v[178:181], v[182:185], v[78:81]
	s_waitcnt lgkmcnt(0)
	global_store_dwordx4 v[82:83], v[70:73], off
	s_nop 1
	v_mul_f32_e32 v70, v68, v75
	v_cvt_pk_bf16_f32 v70, v69, v70
	v_mul_f32_e32 v69, v68, v76
	v_mul_f32_e32 v71, v68, v77
	v_cvt_pk_bf16_f32 v71, v69, v71
	ds_write_b64 v150, v[70:71] offset:2304
	v_mul_f32_e32 v69, v68, v86
	v_mul_f32_e32 v70, v68, v87
	v_cvt_pk_bf16_f32 v70, v69, v70
	v_mul_f32_e32 v69, v68, v88
	v_mul_f32_e32 v71, v68, v89
	v_cvt_pk_bf16_f32 v71, v69, v71
	ds_write_b64 v150, v[70:71] offset:2336
	v_mul_f32_e32 v69, v68, v94
	v_mul_f32_e32 v70, v68, v95
	v_cvt_pk_bf16_f32 v70, v69, v70
	v_mul_f32_e32 v69, v68, v96
	v_mul_f32_e32 v71, v68, v97
	v_cvt_pk_bf16_f32 v71, v69, v71
	ds_write_b64 v150, v[70:71] offset:2368
	v_mul_f32_e32 v69, v68, v78
	v_mul_f32_e32 v70, v68, v79
	v_cvt_pk_bf16_f32 v70, v69, v70
	v_mul_f32_e32 v69, v68, v80
	v_mul_f32_e32 v68, v68, v81
	v_cvt_pk_bf16_f32 v71, v69, v68
	ds_write_b64 v150, v[70:71] offset:2400
	ds_read_b128 v[68:71], v153 offset:2304
	v_lshl_add_u64 v[72:73], v[114:115], 0, s[36:37]
	v_lshl_add_u64 v[74:75], v[72:73], 0, v[0:1]
	v_lshl_add_u64 v[72:73], v[72:73], 0, v[142:143]
	s_waitcnt lgkmcnt(0)
	global_store_dwordx4 v[74:75], v[68:71], off
	ds_read_b128 v[68:71], v154 offset:2304
	s_waitcnt lgkmcnt(0)
	global_store_dwordx4 v[72:73], v[68:71], off
	ds_read_b128 v[68:71], v155
	ds_read_b128 v[72:75], v155 offset:64
	ds_read_b128 v[76:79], v155 offset:2304
	ds_read_b128 v[80:83], v155 offset:2368
	s_waitcnt lgkmcnt(3)
	v_mfma_f32_16x16x32_bf16 v[68:71], v[68:71], v[48:51], 0
	s_waitcnt lgkmcnt(2)
	v_mfma_f32_16x16x32_bf16 v[116:119], v[72:75], v[44:47], v[68:71]
	s_nop 5
	ds_read_b128 v[68:71], v155 offset:4608
	ds_read_b128 v[72:75], v155 offset:4672
	v_cndmask_b32_e64 v113, v197, v116, s[50:51]
	s_waitcnt lgkmcnt(3)
	v_mfma_f32_16x16x32_bf16 v[84:87], v[76:79], v[48:51], 0
	v_cndmask_b32_e64 v145, v197, v117, s[52:53]
	v_max3_f32 v116, v113, s78, v145
	v_cndmask_b32_e64 v118, v197, v118, s[54:55]
	v_mfma_f32_16x16x32_bf16 v[76:79], v[76:79], v[56:59], 0
	v_cndmask_b32_e64 v119, v197, v119, s[56:57]
	v_max3_f32 v116, v116, v118, v119
	s_waitcnt lgkmcnt(2)
	v_mfma_f32_16x16x32_bf16 v[120:123], v[80:83], v[44:47], v[84:87]
	v_mfma_f32_16x16x32_bf16 v[80:83], v[80:83], v[52:55], v[76:79]
	s_nop 2
	ds_read_b128 v[76:79], v155 offset:6912
	ds_read_b128 v[88:91], v155 offset:6976
	s_nop 1
	v_cndmask_b32_e64 v120, v197, v120, s[60:61]
	v_cndmask_b32_e64 v121, v197, v121, s[60:61]
	s_waitcnt lgkmcnt(3)
	v_mfma_f32_16x16x32_bf16 v[84:87], v[68:71], v[48:51], 0
	v_max3_f32 v116, v116, v120, v121
	v_cndmask_b32_e64 v122, v197, v122, s[60:61]
	v_cndmask_b32_e64 v123, v197, v123, s[60:61]
	v_mfma_f32_16x16x32_bf16 v[68:71], v[68:71], v[56:59], 0
	v_max3_f32 v116, v116, v122, v123
	v_cndmask_b32_e64 v82, v197, v82, s[54:55]
	v_cndmask_b32_e64 v83, v197, v83, s[56:57]
	s_waitcnt lgkmcnt(2)
; #define LAS __attribute__((address_space(3)))
; #define LAS __attribute__((address_space(3)))
; #define ATT_LDK(t) do { kfr[t][0] = *(const LAS bf16x8*)(kp0 + (t) * 16 * 72); kfr[t][1] = *(const LAS bf16x8*)(kp0 + (t) * 16 * 72 + 32); } while (0)
; __device__ __forceinline__ void attn_phase(LAS unsigned char* lds, const bf16* PROJ, bf16* CONCAT, const float* sinks) {
;     ...
;     const bool xmap = (gridDim.x == 256);
;     ...
;         for (int p = 0; p < 2; ++p) {
;             const int q16a = (wave & 1) * 4 + 2 * p, kt0 = q16a;
;             f32x4 st[2][10];
;             bf16x8 kfr[10][2];
;             const LAS bf16* kp0 = Ks + (16 * kt0 + fr) * 72 + 8 * fq;
;     ...
;             ATT_LDK(0);
; #pragma unroll
;             for (int t = 0; t < 10; ++t) {
;                 if (t + 1 < 10) ATT_LDK(t + 1);
; #pragma unroll
;                 for (int x = 0; x < 2; ++x) {
;                     if (x + 8 - t == 9 || x + 8 - t == -1) { st[x][t] = (f32x4){-1e30f, -1e30f, -1e30f, -1e30f}; continue; }
;                     f32x4 acc = (f32x4){0.f, 0.f, 0.f, 0.f};
;                     acc = __builtin_amdgcn_mfma_f32_16x16x32_bf16(kfr[t][0], qf[2 * p + x][0], acc, 0, 0, 0);
;                     acc = __builtin_amdgcn_mfma_f32_16x16x32_bf16(kfr[t][1], qf[2 * p + x][1], acc, 0, 0, 0);
;                     st[x][t] = acc;
;                 }
;             }
;     ...
;             float inv[2];
; #pragma unroll
;             for (int x = 0; x < 2; ++x) {
;                 float mx = -1e30f;
; #pragma unroll
;                 for (int t = 0; t < 10; ++t) {
;                     const int D = x + 8 - t;
;                     if (D == 9 || D == -1) continue;
;                     const bool tile_off = firstblk && (kt0 + t < 8);
; #pragma unroll
;                     for (int r = 0; r < 4; ++r) { const int dl = fr - 4 * fq - r;
;                         bool valid = !tile_off;
;                         if (D == 8) valid = valid && (dl < 0);
;                         if (D == 0) valid = valid && (dl >= 0);
;                         const float sv = valid ? st[x][t][r] : -1e30f; st[x][t][r] = sv; mx = fmaxf(mx, sv); }
	v_mfma_f32_16x16x32_bf16 v[124:127], v[72:75], v[44:47], v[84:87]
	v_mfma_f32_16x16x32_bf16 v[84:87], v[72:75], v[52:55], v[68:71]
	s_nop 2
	ds_read_b128 v[68:71], v155 offset:9216
	ds_read_b128 v[72:75], v155 offset:9280
	s_nop 1
	v_cndmask_b32_e64 v124, v197, v124, s[58:59]
	v_cndmask_b32_e64 v125, v197, v125, s[58:59]
	s_waitcnt lgkmcnt(3)
	v_mfma_f32_16x16x32_bf16 v[92:95], v[76:79], v[48:51], 0
	v_max3_f32 v116, v116, v124, v125
	v_cndmask_b32_e64 v126, v197, v126, s[58:59]
	v_cndmask_b32_e64 v127, v197, v127, s[58:59]
	v_mfma_f32_16x16x32_bf16 v[76:79], v[76:79], v[56:59], 0
	v_max3_f32 v116, v116, v126, v127
	v_cndmask_b32_e64 v84, v197, v84, s[58:59]
	v_cndmask_b32_e64 v85, v197, v85, s[58:59]
	s_waitcnt lgkmcnt(2)
	v_mfma_f32_16x16x32_bf16 v[158:161], v[88:91], v[44:47], v[92:95]
	v_cndmask_b32_e64 v86, v197, v86, s[58:59]
	v_cndmask_b32_e64 v87, v197, v87, s[58:59]
	v_mfma_f32_16x16x32_bf16 v[88:91], v[88:91], v[52:55], v[76:79]
	s_nop 2
	ds_read_b128 v[76:79], v155 offset:11520
	ds_read_b128 v[96:99], v155 offset:11584
	v_cndmask_b32_e64 v146, v197, v158, s[58:59]
	s_nop 1
	v_cndmask_b32_e64 v88, v197, v88, s[58:59]
	s_waitcnt lgkmcnt(3)
	v_mfma_f32_16x16x32_bf16 v[92:95], v[68:71], v[48:51], 0
	v_cndmask_b32_e64 v89, v197, v89, s[58:59]
	v_cndmask_b32_e64 v90, v197, v90, s[58:59]
	v_cndmask_b32_e64 v91, v197, v91, s[58:59]
	v_mfma_f32_16x16x32_bf16 v[68:71], v[68:71], v[56:59], 0
	s_waitcnt lgkmcnt(2)
	v_mfma_f32_16x16x32_bf16 v[174:177], v[72:75], v[44:47], v[92:95]
	v_mfma_f32_16x16x32_bf16 v[92:95], v[72:75], v[52:55], v[68:71]
	s_nop 4
	ds_read_b128 v[68:71], v155 offset:13824
	ds_read_b128 v[72:75], v155 offset:13888
	v_cndmask_b32_e64 v190, v197, v177, s[58:59]
	v_cndmask_b32_e64 v92, v197, v92, s[58:59]
	s_waitcnt lgkmcnt(3)
	v_mfma_f32_16x16x32_bf16 v[100:103], v[76:79], v[48:51], 0
	v_cndmask_b32_e64 v93, v197, v93, s[58:59]
	v_cndmask_b32_e64 v94, v197, v94, s[58:59]
	v_cndmask_b32_e64 v95, v197, v95, s[58:59]
	v_mfma_f32_16x16x32_bf16 v[76:79], v[76:79], v[56:59], 0
	s_waitcnt lgkmcnt(2)
	v_mfma_f32_16x16x32_bf16 v[178:181], v[96:99], v[44:47], v[100:103]
	v_mfma_f32_16x16x32_bf16 v[96:99], v[96:99], v[52:55], v[76:79]
	s_nop 4
	ds_read_b128 v[76:79], v155 offset:16128
	ds_read_b128 v[100:103], v155 offset:16192
	ds_read_b128 v[182:185], v155 offset:18432
	ds_read_b128 v[186:189], v155 offset:18496
	v_cndmask_b32_e64 v191, v197, v178, s[58:59]
	s_waitcnt lgkmcnt(5)
	v_mfma_f32_16x16x32_bf16 v[104:107], v[68:71], v[48:51], 0
	v_cndmask_b32_e64 v199, v197, v179, s[58:59]
	v_mfma_f32_16x16x32_bf16 v[68:71], v[68:71], v[56:59], 0
	s_waitcnt lgkmcnt(4)
	v_mfma_f32_16x16x32_bf16 v[108:111], v[72:75], v[44:47], v[104:107]
	v_mfma_f32_16x16x32_bf16 v[68:71], v[72:75], v[52:55], v[68:71]
	s_waitcnt lgkmcnt(3)
	v_mfma_f32_16x16x32_bf16 v[72:75], v[76:79], v[48:51], 0
	s_waitcnt lgkmcnt(2)
	v_mfma_f32_16x16x32_bf16 v[104:107], v[100:103], v[44:47], v[72:75]
	v_mfma_f32_16x16x32_bf16 v[72:75], v[76:79], v[56:59], 0
	s_waitcnt lgkmcnt(1)
	v_mfma_f32_16x16x32_bf16 v[76:79], v[182:185], v[48:51], 0
	v_mfma_f32_16x16x32_bf16 v[72:75], v[100:103], v[52:55], v[72:75]
	ds_read_b128 v[100:103], v155 offset:20736
	ds_read_b128 v[200:203], v155 offset:20800
	s_waitcnt lgkmcnt(2)
	v_mfma_f32_16x16x32_bf16 v[208:211], v[186:189], v[44:47], v[76:79]
	v_mfma_f32_16x16x32_bf16 v[76:79], v[182:185], v[56:59], 0
	v_cndmask_b32_e64 v184, v197, v159, s[58:59]
	v_max3_f32 v116, v116, v146, v184
	v_cndmask_b32_e64 v185, v197, v160, s[58:59]
	v_mfma_f32_16x16x32_bf16 v[76:79], v[186:189], v[52:55], v[76:79]
	v_cndmask_b32_e64 v186, v197, v161, s[58:59]
	v_max3_f32 v116, v116, v185, v186
	v_cndmask_b32_e64 v187, v197, v174, s[58:59]
	s_waitcnt lgkmcnt(1)
	v_mfma_f32_16x16x32_bf16 v[100:103], v[100:103], v[56:59], 0
	v_cndmask_b32_e64 v188, v197, v175, s[58:59]
	v_max3_f32 v116, v116, v187, v188
	v_cndmask_b32_e64 v189, v197, v176, s[58:59]
	v_max3_f32 v116, v116, v189, v190
	s_waitcnt lgkmcnt(0)
	v_mfma_f32_16x16x32_bf16 v[100:103], v[200:203], v[52:55], v[100:103]
	s_andn2_b64 vcc, exec, s[64:65]
	s_cbranch_vccnz .Lattn_q_skip
	s_and_b32 s98, s17, 7
	s_lshl_b32 s98, s98, 7
	s_bfe_u32 s99, s17, 0x10009
	s_lshl_b32 s99, s99, 6
	s_or_b32 s98, s98, s99
	s_bfe_u32 s99, s17, 0x50003
	s_lshl_b32 s99, s99, 1
	s_or_b32 s98, s98, s99
	s_bfe_u32 s99, s17, 0x10008
	s_or_b32 s98, s98, s99
	s_and_b64 vcc, s[80:81], exec
	s_cselect_b32 s98, s98, s17
	s_ashr_i32 s100, s98, 7
	s_ashr_i32 s101, s100, 31
	s_lshl_b32 s99, s98, 6
	s_lshl_b64 s[100:101], s[100:101], 13
	s_and_b32 s99, s99, 0x1f80
	s_or_b32 s99, s100, s99
	v_or_b32_e32 v30, s99, v132
	s_lshl_b32 s99, s98, 2
	s_and_b32 s99, s99, 4
	v_add_u32_e32 v250, s99, v133
	v_ashrrev_i32_e32 v251, 31, v250
	v_lshl_add_u64 v[250:251], v[250:251], 2, s[0:1]
	global_load_dword v249, v[250:251], off
	v_add_lshl_u32 v28, s99, v133, 6
	v_ashrrev_i32_e32 v29, 31, v28
	v_lshl_add_u64 v[28:29], v[28:29], 1, v[140:141]
	v_mad_u64_u32 v[52:53], vcc, v30, s85, v[28:29]
	v_mad_i32_i24 v53, s101, v195, v53
	v_add_co_u32_e32 v36, vcc, 0xa000, v52
	global_load_dwordx4 v[32:35], v[52:53], off nt
	global_load_dwordx4 v[28:31], v[52:53], off offset:64 nt
	v_addc_co_u32_e32 v37, vcc, 0, v53, vcc
	v_add_co_u32_e32 v44, vcc, 0x14000, v52
	global_load_dwordx4 v[40:43], v[36:37], off nt
	s_nop 0
	global_load_dwordx4 v[36:39], v[36:37], off offset:64 nt
	v_addc_co_u32_e32 v45, vcc, 0, v53, vcc
	v_add_co_u32_e32 v52, vcc, 0x1e000, v52
	global_load_dwordx4 v[48:51], v[44:45], off nt
	s_nop 0
	global_load_dwordx4 v[44:47], v[44:45], off offset:64 nt
	v_addc_co_u32_e32 v53, vcc, 0, v53, vcc
	global_load_dwordx4 v[56:59], v[52:53], off nt
	s_nop 0
	global_load_dwordx4 v[52:55], v[52:53], off offset:64 nt
